# NA: first-tile deferred rescale skips the alpha exchange and the o *= alpha multiplies when every row maximum is still -1e30
# speedup vs baseline: 1.0020x; 1.0008x over previous
; #define QK_LD(d) do { const int a_ = kb + (((d) * 32 + hb) ^ xs); B0[d] = lds_rd128<0>(a_); B1[d] = lds_rd128<8192>(a_); Q[d] = lds_rd128<(d) * 1024>(qb); } while (0)
; #define QK_MM(d, W) do { asm volatile("s_waitcnt lgkmcnt(" #W ")" : "+v"(B0[d]), "+v"(B1[d]), "+v"(Q[d]) :: "memory"); \
;     p0 = __builtin_amdgcn_mfma_f32_32x32x16_bf16(B0[d], Q[d], (d) == 0 ? zv : p0, 0, 0, 0); p1 = __builtin_amdgcn_mfma_f32_32x32x16_bf16(B1[d], Q[d], (d) == 0 ? zv : p1, 0, 0, 0); } while (0)
; __device__ __forceinline__ void qkt128(f32x16& p0, f32x16& p1, const char* Ks, const char* Ql, int r32, int hi, const f32x16& zv) {
;   const int kb = (int)(uintptr_t)Ks + r32 * 256, xs = (r32 & 7) << 4, hb = hi * 16, qb = (int)(uintptr_t)Ql;
;   bf16x8 B0[8], B1[8], Q[8];
;     ...
;   QK_LD(0); QK_LD(1); QK_LD(2);
;   QK_MM(0, 6); QK_LD(3); QK_MM(1, 6); QK_LD(4); QK_MM(2, 6); QK_LD(5); QK_MM(3, 6); QK_LD(6); QK_MM(4, 6); QK_LD(7); QK_MM(5, 6); QK_MM(6, 3); QK_MM(7, 0);
.LBB0_519:
	s_add_i32 s53, s87, s2
	s_add_i32 s52, s53, -6
	s_cmp_ge_u32 s52, s86
	s_cselect_b64 s[64:65], -1, 0
	s_cmp_lt_u32 s52, s54
	s_cselect_b64 vcc, -1, 0
	s_and_b64 s[64:65], s[64:65], vcc
	s_andn2_b64 vcc, exec, s[64:65]
	s_cbranch_vccnz .LBB0_524
	ds_read_b128 v[98:101], v174 offset:0
	ds_read_b128 v[198:201], v174 offset:0x2000
	ds_read_b128 v[202:205], v162 offset:0
	ds_read_b128 v[206:209], v175 offset:0
	ds_read_b128 v[210:213], v175 offset:0x2000
	ds_read_b128 v[214:217], v162 offset:0x400
	ds_read_b128 v[218:221], v176 offset:0
	ds_read_b128 v[222:225], v176 offset:0x2000
	ds_read_b128 v[226:229], v162 offset:0x800
	s_nop 0
	s_waitcnt lgkmcnt(6)
	s_nop 0
	v_mfma_f32_32x32x16_bf16 v[82:97], v[98:101], v[202:205], v[2:17]
	v_mfma_f32_32x32x16_bf16 v[98:113], v[198:201], v[202:205], v[2:17]
	ds_read_b128 v[198:201], v177 offset:0
	ds_read_b128 v[202:205], v177 offset:0x2000
	ds_read_b128 v[230:233], v162 offset:0xc00
	s_waitcnt lgkmcnt(6)
	s_nop 0
	v_mfma_f32_32x32x16_bf16 v[98:113], v[210:213], v[214:217], v[98:113]
	v_mfma_f32_32x32x16_bf16 v[82:97], v[206:209], v[214:217], v[82:97]
	ds_read_b128 v[206:209], v178 offset:0
	ds_read_b128 v[210:213], v178 offset:0x2000
	ds_read_b128 v[214:217], v162 offset:0x1000
	s_waitcnt lgkmcnt(6)
	s_nop 0
	v_mfma_f32_32x32x16_bf16 v[98:113], v[222:225], v[226:229], v[98:113]
	v_mfma_f32_32x32x16_bf16 v[82:97], v[218:221], v[226:229], v[82:97]
	ds_read_b128 v[218:221], v179 offset:0
	ds_read_b128 v[222:225], v179 offset:0x2000
	ds_read_b128 v[226:229], v162 offset:0x1400
	s_waitcnt lgkmcnt(6)
	s_nop 0
	v_mfma_f32_32x32x16_bf16 v[98:113], v[202:205], v[230:233], v[98:113]
	v_mfma_f32_32x32x16_bf16 v[82:97], v[198:201], v[230:233], v[82:97]
	ds_read_b128 v[198:201], v180 offset:0
	ds_read_b128 v[202:205], v180 offset:0x2000
	ds_read_b128 v[230:233], v162 offset:0x1800
	s_waitcnt lgkmcnt(6)
	s_nop 0
	v_mfma_f32_32x32x16_bf16 v[98:113], v[210:213], v[214:217], v[98:113]
	v_mfma_f32_32x32x16_bf16 v[82:97], v[206:209], v[214:217], v[82:97]
	ds_read_b128 v[206:209], v181 offset:0
	ds_read_b128 v[210:213], v181 offset:0x2000
	ds_read_b128 v[214:217], v162 offset:0x1c00
	s_waitcnt lgkmcnt(6)
	s_waitcnt lgkmcnt(3)
	s_nop 0
	s_waitcnt lgkmcnt(0)
	v_mfma_f32_32x32x16_bf16 v[98:113], v[222:225], v[226:229], v[98:113]
	v_mfma_f32_32x32x16_bf16 v[82:97], v[218:221], v[226:229], v[82:97]
	v_mfma_f32_32x32x16_bf16 v[98:113], v[202:205], v[230:233], v[98:113]
	v_mfma_f32_32x32x16_bf16 v[82:97], v[198:201], v[230:233], v[82:97]
	v_mfma_f32_32x32x16_bf16 v[98:113], v[210:213], v[214:217], v[98:113]
	v_mfma_f32_32x32x16_bf16 v[82:97], v[206:209], v[214:217], v[82:97]
	s_nop 11
	ds_read2_b32 v[82:83], v193 offset0:8 offset1:9
	ds_read2_b32 v[84:85], v193 offset0:10 offset1:11
	ds_read2_b32 v[86:87], v193 offset0:16 offset1:17
	ds_read2_b32 v[88:89], v193 offset0:18 offset1:19
	ds_read2_b32 v[90:91], v193 offset0:24 offset1:25
	ds_read2_b32 v[204:205], v193 offset0:26 offset1:27
	ds_read2_b32 v[206:207], v193 offset0:32 offset1:33
	ds_read2_b32 v[208:209], v193 offset0:34 offset1:35
	ds_read2_b32 v[210:211], v193 offset1:1
	ds_read2_b32 v[212:213], v193 offset0:2 offset1:3
	s_waitcnt lgkmcnt(9)
	s_waitcnt lgkmcnt(8)
	s_waitcnt lgkmcnt(7)
	v_add_f32_e32 v82, v98, v82
	v_cndmask_b32_e64 v202, v195, v82, s[6:7]
	v_add_f32_e32 v82, v99, v83
	v_cndmask_b32_e64 v201, v195, v82, s[8:9]
	v_add_f32_e32 v82, v100, v84
	v_cndmask_b32_e64 v200, v195, v82, s[10:11]
	v_add_f32_e32 v82, v101, v85
	v_cndmask_b32_e64 v199, v195, v82, s[12:13]
	v_add_f32_e32 v82, v102, v86
	v_cndmask_b32_e64 v101, v195, v82, s[14:15]
	v_add_f32_e32 v82, v103, v87
	s_waitcnt lgkmcnt(6)
	v_cndmask_b32_e64 v100, v195, v82, s[16:17]
	v_add_f32_e32 v82, v104, v88
	v_cndmask_b32_e64 v99, v195, v82, s[18:19]
	v_add_f32_e32 v82, v105, v89
	s_waitcnt lgkmcnt(5)
	v_cndmask_b32_e64 v98, v195, v82, s[20:21]
	v_add_f32_e32 v82, v106, v90
	v_cndmask_b32_e64 v93, v195, v82, s[22:23]
	v_add_f32_e32 v82, v107, v91
	s_waitcnt lgkmcnt(4)
	v_cndmask_b32_e64 v92, v195, v82, s[24:25]
	v_add_f32_e32 v82, v108, v204
	v_cndmask_b32_e64 v91, v195, v82, s[26:27]
	v_add_f32_e32 v82, v109, v205
	s_waitcnt lgkmcnt(3)
	v_cndmask_b32_e64 v90, v195, v82, s[28:29]
	v_add_f32_e32 v82, v110, v206
	v_cndmask_b32_e64 v89, v195, v82, s[30:31]
	v_add_f32_e32 v82, v111, v207
	s_waitcnt lgkmcnt(2)
	v_cndmask_b32_e64 v88, v195, v82, s[34:35]
	v_add_f32_e32 v82, v112, v208
	s_waitcnt lgkmcnt(1)
	s_waitcnt lgkmcnt(0)
	v_cndmask_b32_e64 v87, v195, v82, s[36:37]
	v_add_f32_e32 v82, v113, v209
	v_add_f32_e32 v84, v96, v212
	v_add_f32_e32 v85, v97, v213
	v_cndmask_b32_e64 v86, v195, v82, s[38:39]
	v_add_f32_e32 v82, v94, v210
	v_add_f32_e32 v83, v95, v211
	v_cndmask_b32_e64 v84, v195, v84, s[44:45]
	v_cndmask_b32_e64 v85, v195, v85, s[46:47]
	v_cndmask_b32_e64 v82, v195, v82, s[40:41]
	v_cndmask_b32_e64 v83, v195, v83, s[42:43]
	v_max_f32_e32 v94, v84, v85
	v_max3_f32 v94, v82, v83, v94
	v_max3_f32 v94, v94, v202, v201
	v_max3_f32 v94, v94, v200, v199
	v_max3_f32 v94, v94, v101, v100
	v_max3_f32 v94, v94, v99, v98
	v_max3_f32 v94, v94, v93, v92
	v_max3_f32 v94, v94, v91, v90
	v_max3_f32 v94, v94, v89, v88
	v_max3_f32 v94, v94, v87, v86
	v_mov_b32_e32 v95, v94
	s_nop 1
	v_permlane32_swap_b32_e32 v94, v95
	v_max_f32_e32 v95, v95, v95
	v_max_f32_e32 v94, v94, v94
	v_max_f32_e32 v94, v94, v95
	v_sub_f32_e32 v95, v94, v197
	v_cmp_ge_f32_e32 vcc, s88, v95
	s_cmp_eq_u64 vcc, exec
	s_cbranch_scc1 .LBB0_525
	v_max_f32_e32 v94, v94, v94
	v_max_f32_e32 v95, v197, v197
	v_max_f32_e32 v198, v95, v94
	v_sub_f32_e32 v94, v197, v198
	v_exp_f32_e32 v94, v94
	v_cmp_eq_f32_e32 vcc, 0xf149f2ca, v197
	s_cmp_eq_u64 vcc, exec
	s_cbranch_scc1 .LBB0_526
	s_and_saveexec_b64 s[64:65], s[48:49]
	ds_write_b32 v182, v94 offset:128
	s_or_b64 exec, exec, s[64:65]
	s_waitcnt lgkmcnt(0)
	v_mul_f32_e32 v169, v169, v94
	ds_read_b128 v[94:97], v183 offset:128
	ds_read_b128 v[102:105], v183 offset:160
	ds_read_b128 v[106:109], v183 offset:192
	ds_read_b128 v[110:113], v183 offset:224
	s_waitcnt lgkmcnt(3)
	v_pk_mul_f32 v[68:69], v[68:69], v[96:97]
	s_waitcnt lgkmcnt(2)
	v_pk_mul_f32 v[72:73], v[72:73], v[104:105]
	s_waitcnt lgkmcnt(1)
	v_pk_mul_f32 v[76:77], v[76:77], v[108:109]
	s_waitcnt lgkmcnt(0)
	v_pk_mul_f32 v[80:81], v[80:81], v[112:113]
	v_pk_mul_f32 v[78:79], v[78:79], v[110:111]
	v_pk_mul_f32 v[74:75], v[74:75], v[106:107]
	v_pk_mul_f32 v[70:71], v[70:71], v[102:103]
	v_pk_mul_f32 v[66:67], v[66:67], v[94:95]
	v_pk_mul_f32 v[64:65], v[64:65], v[112:113]
	v_pk_mul_f32 v[60:61], v[60:61], v[108:109]
	v_pk_mul_f32 v[56:57], v[56:57], v[104:105]
	v_pk_mul_f32 v[52:53], v[52:53], v[96:97]
	v_pk_mul_f32 v[62:63], v[62:63], v[110:111]
	v_pk_mul_f32 v[58:59], v[58:59], v[106:107]
	v_pk_mul_f32 v[54:55], v[54:55], v[102:103]
	v_pk_mul_f32 v[50:51], v[50:51], v[94:95]
	v_pk_mul_f32 v[48:49], v[48:49], v[112:113]
	v_pk_mul_f32 v[44:45], v[44:45], v[108:109]
	v_pk_mul_f32 v[40:41], v[40:41], v[104:105]
	v_pk_mul_f32 v[36:37], v[36:37], v[96:97]
	v_pk_mul_f32 v[46:47], v[46:47], v[110:111]
	v_pk_mul_f32 v[42:43], v[42:43], v[106:107]
	v_pk_mul_f32 v[38:39], v[38:39], v[102:103]
	v_pk_mul_f32 v[34:35], v[34:35], v[94:95]
	v_pk_mul_f32 v[32:33], v[32:33], v[112:113]
	v_pk_mul_f32 v[28:29], v[28:29], v[108:109]
	v_pk_mul_f32 v[24:25], v[24:25], v[104:105]
	v_pk_mul_f32 v[20:21], v[20:21], v[96:97]
	v_pk_mul_f32 v[30:31], v[30:31], v[110:111]
	v_pk_mul_f32 v[26:27], v[26:27], v[106:107]
	v_pk_mul_f32 v[22:23], v[22:23], v[102:103]
	v_pk_mul_f32 v[18:19], v[18:19], v[94:95]
	s_branch .LBB0_526

; #define QK_LD(d) do { const int a_ = kb + (((d) * 32 + hb) ^ xs); B0[d] = lds_rd128<0>(a_); B1[d] = lds_rd128<8192>(a_); Q[d] = lds_rd128<(d) * 1024>(qb); } while (0)
; #define QK_MM(d, W) do { asm volatile("s_waitcnt lgkmcnt(" #W ")" : "+v"(B0[d]), "+v"(B1[d]), "+v"(Q[d]) :: "memory"); \
;     p0 = __builtin_amdgcn_mfma_f32_32x32x16_bf16(B0[d], Q[d], (d) == 0 ? zv : p0, 0, 0, 0); p1 = __builtin_amdgcn_mfma_f32_32x32x16_bf16(B1[d], Q[d], (d) == 0 ? zv : p1, 0, 0, 0); } while (0)
; __device__ __forceinline__ void qkt128(f32x16& p0, f32x16& p1, const char* Ks, const char* Ql, int r32, int hi, const f32x16& zv) {
;   const int kb = (int)(uintptr_t)Ks + r32 * 256, xs = (r32 & 7) << 4, hb = hi * 16, qb = (int)(uintptr_t)Ql;
;   bf16x8 B0[8], B1[8], Q[8];
;     ...
;   QK_LD(0); QK_LD(1); QK_LD(2);
;   QK_MM(0, 6); QK_LD(3); QK_MM(1, 6); QK_LD(4); QK_MM(2, 6); QK_LD(5); QK_MM(3, 6); QK_LD(6); QK_MM(4, 6); QK_LD(7); QK_MM(5, 6); QK_MM(6, 3); QK_MM(7, 0);
.LBB0_530:
	s_andn2_b64 vcc, exec, s[64:65]
	s_mov_b64 s[64:65], -1
	s_waitcnt lgkmcnt(0)
	s_barrier
	s_cbranch_vccnz .LBB0_536
	s_add_i32 s53, s53, -5
	s_cmp_ge_u32 s53, s86
	s_cselect_b64 s[64:65], -1, 0
	s_cmp_lt_u32 s52, s55
	s_cselect_b64 s[52:53], -1, 0
	s_and_b64 s[52:53], s[64:65], s[52:53]
	s_andn2_b64 vcc, exec, s[52:53]
	s_cbranch_vccnz .LBB0_537
	ds_read_b128 v[98:101], v184 offset:0
	ds_read_b128 v[200:203], v184 offset:0x2000
	ds_read_b128 v[204:207], v162 offset:0
	ds_read_b128 v[208:211], v185 offset:0
	ds_read_b128 v[212:215], v185 offset:0x2000
	ds_read_b128 v[216:219], v162 offset:0x400
	ds_read_b128 v[220:223], v186 offset:0
	ds_read_b128 v[224:227], v186 offset:0x2000
	ds_read_b128 v[228:231], v162 offset:0x800
	s_nop 0
	s_waitcnt lgkmcnt(6)
	s_nop 0
	v_mfma_f32_32x32x16_bf16 v[82:97], v[98:101], v[204:207], v[2:17]
	v_mfma_f32_32x32x16_bf16 v[98:113], v[200:203], v[204:207], v[2:17]
	ds_read_b128 v[200:203], v187 offset:0
	ds_read_b128 v[204:207], v187 offset:0x2000
	ds_read_b128 v[232:235], v162 offset:0xc00
	s_waitcnt lgkmcnt(6)
	s_nop 0
	v_mfma_f32_32x32x16_bf16 v[98:113], v[212:215], v[216:219], v[98:113]
	v_mfma_f32_32x32x16_bf16 v[82:97], v[208:211], v[216:219], v[82:97]
	ds_read_b128 v[208:211], v188 offset:0
	ds_read_b128 v[212:215], v188 offset:0x2000
	ds_read_b128 v[216:219], v162 offset:0x1000
	s_waitcnt lgkmcnt(6)
	s_nop 0
	v_mfma_f32_32x32x16_bf16 v[98:113], v[224:227], v[228:231], v[98:113]
	v_mfma_f32_32x32x16_bf16 v[82:97], v[220:223], v[228:231], v[82:97]
	ds_read_b128 v[220:223], v189 offset:0
	ds_read_b128 v[224:227], v189 offset:0x2000
	ds_read_b128 v[228:231], v162 offset:0x1400
	s_waitcnt lgkmcnt(6)
	s_nop 0
	v_mfma_f32_32x32x16_bf16 v[98:113], v[204:207], v[232:235], v[98:113]
	v_mfma_f32_32x32x16_bf16 v[82:97], v[200:203], v[232:235], v[82:97]
	ds_read_b128 v[200:203], v190 offset:0
	ds_read_b128 v[204:207], v190 offset:0x2000
	ds_read_b128 v[232:235], v162 offset:0x1800
	s_waitcnt lgkmcnt(6)
	s_nop 0
	v_mfma_f32_32x32x16_bf16 v[98:113], v[212:215], v[216:219], v[98:113]
	v_mfma_f32_32x32x16_bf16 v[82:97], v[208:211], v[216:219], v[82:97]
	ds_read_b128 v[208:211], v191 offset:0
	ds_read_b128 v[212:215], v191 offset:0x2000
	ds_read_b128 v[216:219], v162 offset:0x1c00
	s_waitcnt lgkmcnt(6)
	s_waitcnt lgkmcnt(3)
	s_nop 0
	s_waitcnt lgkmcnt(0)
	v_mfma_f32_32x32x16_bf16 v[98:113], v[224:227], v[228:231], v[98:113]
	v_mfma_f32_32x32x16_bf16 v[82:97], v[220:223], v[228:231], v[82:97]
	v_mfma_f32_32x32x16_bf16 v[98:113], v[204:207], v[232:235], v[98:113]
	v_mfma_f32_32x32x16_bf16 v[82:97], v[200:203], v[232:235], v[82:97]
	v_mfma_f32_32x32x16_bf16 v[98:113], v[212:215], v[216:219], v[98:113]
	v_mfma_f32_32x32x16_bf16 v[82:97], v[208:211], v[216:219], v[82:97]
	s_nop 11
	ds_read2_b32 v[82:83], v193 offset0:136 offset1:137
	ds_read2_b32 v[84:85], v193 offset0:138 offset1:139
	ds_read2_b32 v[86:87], v193 offset0:144 offset1:145
	ds_read2_b32 v[88:89], v193 offset0:146 offset1:147
	ds_read2_b32 v[90:91], v193 offset0:152 offset1:153
	ds_read2_b32 v[204:205], v193 offset0:154 offset1:155
	ds_read2_b32 v[206:207], v193 offset0:160 offset1:161
	ds_read2_b32 v[208:209], v193 offset0:162 offset1:163
	ds_read2_b32 v[210:211], v193 offset0:128 offset1:129
	ds_read2_b32 v[212:213], v193 offset0:130 offset1:131
	s_waitcnt lgkmcnt(9)
	s_waitcnt lgkmcnt(8)
	s_waitcnt lgkmcnt(7)
	v_add_f32_e32 v82, v98, v82
	v_cndmask_b32_e64 v202, v195, v82, s[6:7]
	v_add_f32_e32 v82, v99, v83
	v_cndmask_b32_e64 v201, v195, v82, s[8:9]
	v_add_f32_e32 v82, v100, v84
	v_cndmask_b32_e64 v200, v195, v82, s[10:11]
	v_add_f32_e32 v82, v101, v85
	v_cndmask_b32_e64 v199, v195, v82, s[12:13]
	v_add_f32_e32 v82, v102, v86
	v_cndmask_b32_e64 v101, v195, v82, s[14:15]
	v_add_f32_e32 v82, v103, v87
	s_waitcnt lgkmcnt(6)
	v_cndmask_b32_e64 v100, v195, v82, s[16:17]
	v_add_f32_e32 v82, v104, v88
	v_cndmask_b32_e64 v99, v195, v82, s[18:19]
	v_add_f32_e32 v82, v105, v89
	s_waitcnt lgkmcnt(5)
	v_cndmask_b32_e64 v98, v195, v82, s[20:21]
	v_add_f32_e32 v82, v106, v90
	v_cndmask_b32_e64 v93, v195, v82, s[22:23]
	v_add_f32_e32 v82, v107, v91
	s_waitcnt lgkmcnt(4)
	v_cndmask_b32_e64 v92, v195, v82, s[24:25]
	v_add_f32_e32 v82, v108, v204
	v_cndmask_b32_e64 v91, v195, v82, s[26:27]
	v_add_f32_e32 v82, v109, v205
	s_waitcnt lgkmcnt(3)
	v_cndmask_b32_e64 v90, v195, v82, s[28:29]
	v_add_f32_e32 v82, v110, v206
	v_cndmask_b32_e64 v89, v195, v82, s[30:31]
	v_add_f32_e32 v82, v111, v207
	s_waitcnt lgkmcnt(2)
	v_cndmask_b32_e64 v88, v195, v82, s[34:35]
	v_add_f32_e32 v82, v112, v208
	s_waitcnt lgkmcnt(1)
	s_waitcnt lgkmcnt(0)
	v_cndmask_b32_e64 v87, v195, v82, s[36:37]
	v_add_f32_e32 v82, v113, v209
	v_add_f32_e32 v84, v96, v212
	v_add_f32_e32 v85, v97, v213
	v_cndmask_b32_e64 v86, v195, v82, s[38:39]
	v_add_f32_e32 v82, v94, v210
	v_add_f32_e32 v83, v95, v211
	v_cndmask_b32_e64 v84, v195, v84, s[44:45]
	v_cndmask_b32_e64 v85, v195, v85, s[46:47]
	v_cndmask_b32_e64 v82, v195, v82, s[40:41]
	v_cndmask_b32_e64 v83, v195, v83, s[42:43]
	v_max_f32_e32 v94, v84, v85
	v_max3_f32 v94, v82, v83, v94
	v_max3_f32 v94, v94, v202, v201
	v_max3_f32 v94, v94, v200, v199
	v_max3_f32 v94, v94, v101, v100
	v_max3_f32 v94, v94, v99, v98
	v_max3_f32 v94, v94, v93, v92
	v_max3_f32 v94, v94, v91, v90
	v_max3_f32 v94, v94, v89, v88
	v_max3_f32 v94, v94, v87, v86
	v_mov_b32_e32 v95, v94
	s_nop 1
	v_permlane32_swap_b32_e32 v94, v95
	v_max_f32_e32 v95, v95, v95
	v_max_f32_e32 v94, v94, v94
	v_max_f32_e32 v94, v94, v95
	v_sub_f32_e32 v95, v94, v198
	v_cmp_ge_f32_e32 vcc, s88, v95
	s_cmp_eq_u64 vcc, exec
	s_cbranch_scc1 .LBB0_538
	v_max_f32_e32 v94, v94, v94
	v_max_f32_e32 v95, v198, v198
	v_max_f32_e32 v197, v95, v94
	v_sub_f32_e32 v94, v198, v197
	v_exp_f32_e32 v94, v94
	v_cmp_eq_f32_e32 vcc, 0xf149f2ca, v198
	s_cmp_eq_u64 vcc, exec
	s_cbranch_scc1 .LBB0_539
	s_and_saveexec_b64 s[64:65], s[48:49]
	ds_write_b32 v182, v94 offset:128
	s_or_b64 exec, exec, s[64:65]
	s_waitcnt lgkmcnt(0)
	v_mul_f32_e32 v169, v169, v94
	ds_read_b128 v[94:97], v183 offset:128
	ds_read_b128 v[102:105], v183 offset:160
	ds_read_b128 v[106:109], v183 offset:192
	ds_read_b128 v[110:113], v183 offset:224
	s_waitcnt lgkmcnt(3)
	v_pk_mul_f32 v[68:69], v[68:69], v[96:97]
	s_waitcnt lgkmcnt(2)
	v_pk_mul_f32 v[72:73], v[72:73], v[104:105]
	s_waitcnt lgkmcnt(1)
	v_pk_mul_f32 v[76:77], v[76:77], v[108:109]
	s_waitcnt lgkmcnt(0)
	v_pk_mul_f32 v[80:81], v[80:81], v[112:113]
	v_pk_mul_f32 v[78:79], v[78:79], v[110:111]
	v_pk_mul_f32 v[74:75], v[74:75], v[106:107]
	v_pk_mul_f32 v[70:71], v[70:71], v[102:103]
	v_pk_mul_f32 v[66:67], v[66:67], v[94:95]
	v_pk_mul_f32 v[64:65], v[64:65], v[112:113]
	v_pk_mul_f32 v[60:61], v[60:61], v[108:109]
	v_pk_mul_f32 v[56:57], v[56:57], v[104:105]
	v_pk_mul_f32 v[52:53], v[52:53], v[96:97]
	v_pk_mul_f32 v[62:63], v[62:63], v[110:111]
	v_pk_mul_f32 v[58:59], v[58:59], v[106:107]
	v_pk_mul_f32 v[54:55], v[54:55], v[102:103]
	v_pk_mul_f32 v[50:51], v[50:51], v[94:95]
	v_pk_mul_f32 v[48:49], v[48:49], v[112:113]
	v_pk_mul_f32 v[44:45], v[44:45], v[108:109]
	v_pk_mul_f32 v[40:41], v[40:41], v[104:105]
	v_pk_mul_f32 v[36:37], v[36:37], v[96:97]
	v_pk_mul_f32 v[46:47], v[46:47], v[110:111]
	v_pk_mul_f32 v[42:43], v[42:43], v[106:107]
	v_pk_mul_f32 v[38:39], v[38:39], v[102:103]
	v_pk_mul_f32 v[34:35], v[34:35], v[94:95]
	v_pk_mul_f32 v[32:33], v[32:33], v[112:113]
	v_pk_mul_f32 v[28:29], v[28:29], v[108:109]
	v_pk_mul_f32 v[24:25], v[24:25], v[104:105]
	v_pk_mul_f32 v[20:21], v[20:21], v[96:97]
	v_pk_mul_f32 v[30:31], v[30:31], v[110:111]
	v_pk_mul_f32 v[26:27], v[26:27], v[106:107]
	v_pk_mul_f32 v[22:23], v[22:23], v[102:103]
	v_pk_mul_f32 v[18:19], v[18:19], v[94:95]
	s_branch .LBB0_539

; #define QK_LD(d) do { const int a_ = kb + (((d) * 32 + hb) ^ xs); B0[d] = lds_rd128<0>(a_); B1[d] = lds_rd128<8192>(a_); Q[d] = lds_rd128<(d) * 1024>(qb); } while (0)
; #define QK_MM(d, W) do { asm volatile("s_waitcnt lgkmcnt(" #W ")" : "+v"(B0[d]), "+v"(B1[d]), "+v"(Q[d]) :: "memory"); \
;     p0 = __builtin_amdgcn_mfma_f32_32x32x16_bf16(B0[d], Q[d], (d) == 0 ? zv : p0, 0, 0, 0); p1 = __builtin_amdgcn_mfma_f32_32x32x16_bf16(B1[d], Q[d], (d) == 0 ? zv : p1, 0, 0, 0); } while (0)
; __device__ __forceinline__ void qkt128(f32x16& p0, f32x16& p1, const char* Ks, const char* Ql, int r32, int hi, const f32x16& zv) {
;   const int kb = (int)(uintptr_t)Ks + r32 * 256, xs = (r32 & 7) << 4, hb = hi * 16, qb = (int)(uintptr_t)Ql;
;   bf16x8 B0[8], B1[8], Q[8];
;     ...
;   QK_LD(0); QK_LD(1); QK_LD(2);
;   QK_MM(0, 6); QK_LD(3); QK_MM(1, 6); QK_LD(4); QK_MM(2, 6); QK_LD(5); QK_MM(3, 6); QK_LD(6); QK_MM(4, 6); QK_LD(7); QK_MM(5, 6); QK_MM(6, 3); QK_MM(7, 0);
.LBB0_548:
	s_add_i32 s52, s87, s55
	s_add_i32 s51, s52, -6
	s_cmp_ge_u32 s51, s86
	s_cselect_b64 s[48:49], -1, 0
	s_cmp_lt_u32 s51, s54
	s_cselect_b64 s[62:63], -1, 0
	s_and_b64 s[48:49], s[48:49], s[62:63]
	s_andn2_b64 vcc, exec, s[48:49]
	s_cbranch_vccnz .LBB0_553
	ds_read_b128 v[82:85], v138 offset:0
	ds_read_b128 v[176:179], v138 offset:0x2000
	ds_read_b128 v[180:183], v162 offset:0
	ds_read_b128 v[184:187], v139 offset:0
	ds_read_b128 v[188:191], v139 offset:0x2000
	ds_read_b128 v[196:199], v162 offset:0x400
	ds_read_b128 v[200:203], v140 offset:0
	ds_read_b128 v[204:207], v140 offset:0x2000
	ds_read_b128 v[208:211], v162 offset:0x800
	s_nop 0
	s_waitcnt lgkmcnt(6)
	s_nop 0
	v_mfma_f32_32x32x16_bf16 v[98:113], v[82:85], v[180:183], v[2:17]
	v_mfma_f32_32x32x16_bf16 v[82:97], v[176:179], v[180:183], v[2:17]
	ds_read_b128 v[176:179], v141 offset:0
	ds_read_b128 v[180:183], v141 offset:0x2000
	ds_read_b128 v[212:215], v162 offset:0xc00
	s_waitcnt lgkmcnt(6)
	s_nop 0
	v_mfma_f32_32x32x16_bf16 v[98:113], v[184:187], v[196:199], v[98:113]
	ds_read_b128 v[184:187], v142 offset:0
	v_mfma_f32_32x32x16_bf16 v[82:97], v[188:191], v[196:199], v[82:97]
	ds_read_b128 v[188:191], v142 offset:0x2000
	ds_read_b128 v[196:199], v162 offset:0x1000
	s_waitcnt lgkmcnt(6)
	s_nop 0
	v_mfma_f32_32x32x16_bf16 v[98:113], v[200:203], v[208:211], v[98:113]
	ds_read_b128 v[200:203], v143 offset:0
	v_mfma_f32_32x32x16_bf16 v[82:97], v[204:207], v[208:211], v[82:97]
	ds_read_b128 v[204:207], v143 offset:0x2000
	ds_read_b128 v[208:211], v162 offset:0x1400
	s_waitcnt lgkmcnt(6)
	s_nop 0
	v_mfma_f32_32x32x16_bf16 v[98:113], v[176:179], v[212:215], v[98:113]
	ds_read_b128 v[176:179], v144 offset:0
	v_mfma_f32_32x32x16_bf16 v[82:97], v[180:183], v[212:215], v[82:97]
	ds_read_b128 v[180:183], v144 offset:0x2000
	ds_read_b128 v[212:215], v162 offset:0x1800
	s_waitcnt lgkmcnt(6)
	s_nop 0
	v_mfma_f32_32x32x16_bf16 v[98:113], v[184:187], v[196:199], v[98:113]
	ds_read_b128 v[184:187], v145 offset:0
	v_mfma_f32_32x32x16_bf16 v[82:97], v[188:191], v[196:199], v[82:97]
	ds_read_b128 v[188:191], v145 offset:0x2000
	ds_read_b128 v[196:199], v162 offset:0x1c00
	s_waitcnt lgkmcnt(6)
	s_waitcnt lgkmcnt(3)
	s_nop 0
	s_waitcnt lgkmcnt(0)
	v_mfma_f32_32x32x16_bf16 v[98:113], v[200:203], v[208:211], v[98:113]
	v_mfma_f32_32x32x16_bf16 v[82:97], v[204:207], v[208:211], v[82:97]
	v_mfma_f32_32x32x16_bf16 v[98:113], v[176:179], v[212:215], v[98:113]
	v_mfma_f32_32x32x16_bf16 v[82:97], v[180:183], v[212:215], v[82:97]
	v_mfma_f32_32x32x16_bf16 v[98:113], v[184:187], v[196:199], v[98:113]
	v_mfma_f32_32x32x16_bf16 v[82:97], v[188:191], v[196:199], v[82:97]
	s_nop 11
	ds_read2_b32 v[86:87], v150 offset1:1
	ds_read2_b32 v[88:89], v150 offset0:2 offset1:3
	ds_read2_b32 v[90:91], v150 offset0:8 offset1:9
	ds_read2_b32 v[92:93], v150 offset0:10 offset1:11
	ds_read2_b32 v[178:179], v150 offset0:16 offset1:17
	ds_read2_b32 v[180:181], v150 offset0:18 offset1:19
	ds_read2_b32 v[182:183], v150 offset0:24 offset1:25
	ds_read2_b32 v[184:185], v150 offset0:26 offset1:27
	ds_read2_b32 v[186:187], v150 offset0:32 offset1:33
	ds_read2_b32 v[188:189], v150 offset0:34 offset1:35
	s_waitcnt lgkmcnt(9)
	s_waitcnt lgkmcnt(8)
	s_waitcnt lgkmcnt(7)
	v_add_f32_e32 v86, v98, v86
	v_cndmask_b32_e64 v176, v1, v86, s[4:5]
	v_add_f32_e32 v86, v99, v87
	v_cndmask_b32_e64 v175, v1, v86, s[6:7]
	v_add_f32_e32 v86, v100, v88
	v_cndmask_b32_e64 v99, v1, v86, s[8:9]
	v_add_f32_e32 v86, v101, v89
	v_cndmask_b32_e64 v98, v1, v86, s[10:11]
	v_add_f32_e32 v86, v102, v90
	v_cndmask_b32_e64 v97, v1, v86, s[12:13]
	v_add_f32_e32 v86, v103, v91
	s_waitcnt lgkmcnt(6)
	s_waitcnt lgkmcnt(5)
	s_waitcnt lgkmcnt(4)
	s_waitcnt lgkmcnt(3)
	s_waitcnt lgkmcnt(2)
	s_waitcnt lgkmcnt(1)
	s_waitcnt lgkmcnt(0)
	v_cndmask_b32_e64 v96, v1, v86, s[14:15]
	v_add_f32_e32 v86, v104, v92
	v_add_f32_e32 v84, v84, v188
	v_add_f32_e32 v85, v85, v189
	v_cndmask_b32_e64 v95, v1, v86, s[16:17]
	v_add_f32_e32 v86, v105, v93
	v_add_f32_e32 v82, v82, v186
	v_add_f32_e32 v83, v83, v187
	v_cndmask_b32_e64 v84, v1, v84, s[42:43]
	v_cndmask_b32_e64 v85, v1, v85, s[44:45]
	v_cndmask_b32_e64 v94, v1, v86, s[18:19]
	v_add_f32_e32 v86, v106, v178
	v_cndmask_b32_e64 v82, v1, v82, s[38:39]
	v_cndmask_b32_e64 v83, v1, v83, s[40:41]
	v_max_f32_e32 v100, v84, v85
	v_cndmask_b32_e64 v93, v1, v86, s[20:21]
	v_add_f32_e32 v86, v107, v179
	v_max3_f32 v100, v82, v83, v100
	v_cndmask_b32_e64 v92, v1, v86, s[22:23]
	v_add_f32_e32 v86, v108, v180
	v_max3_f32 v100, v100, v176, v175
	v_cndmask_b32_e64 v91, v1, v86, s[24:25]
	v_add_f32_e32 v86, v109, v181
	v_max3_f32 v100, v100, v99, v98
	v_cndmask_b32_e64 v90, v1, v86, s[26:27]
	v_add_f32_e32 v86, v110, v182
	v_max3_f32 v100, v100, v97, v96
	v_cndmask_b32_e64 v89, v1, v86, s[28:29]
	v_add_f32_e32 v86, v111, v183
	v_max3_f32 v100, v100, v95, v94
	v_cndmask_b32_e64 v88, v1, v86, s[30:31]
	v_add_f32_e32 v86, v112, v184
	v_max3_f32 v100, v100, v93, v92
	v_cndmask_b32_e64 v87, v1, v86, s[34:35]
	v_add_f32_e32 v86, v113, v185
	v_max3_f32 v100, v100, v91, v90
	v_cndmask_b32_e64 v86, v1, v86, s[36:37]
	v_max3_f32 v100, v100, v89, v88
	v_max3_f32 v100, v100, v87, v86
	v_mov_b32_e32 v101, v100
	s_nop 1
	v_permlane32_swap_b32_e32 v100, v101
	v_max_f32_e32 v101, v101, v101
	v_max_f32_e32 v100, v100, v100
	v_max_f32_e32 v100, v100, v101
	v_sub_f32_e32 v101, v100, v170
	v_cmp_ge_f32_e32 vcc, s88, v101
	s_cmp_eq_u64 vcc, exec
	s_cbranch_scc1 .LBB0_554
	v_max_f32_e32 v100, v100, v100
	v_max_f32_e32 v101, v170, v170
	v_max_f32_e32 v171, v101, v100
	v_sub_f32_e32 v100, v170, v171
	v_exp_f32_e32 v100, v100
	v_cmp_eq_f32_e32 vcc, 0xf149f2ca, v170
	s_cmp_eq_u64 vcc, exec
	s_cbranch_scc1 .LBB0_555
	s_and_saveexec_b64 s[48:49], s[46:47]
	ds_write_b32 v152, v100 offset:128
	s_or_b64 exec, exec, s[48:49]
	s_waitcnt lgkmcnt(0)
	v_mul_f32_e32 v169, v169, v100
	ds_read_b128 v[100:103], v153 offset:128
	ds_read_b128 v[104:107], v153 offset:160
	ds_read_b128 v[108:111], v153 offset:192
	ds_read_b128 v[178:181], v153 offset:224
	s_waitcnt lgkmcnt(3)
	v_pk_mul_f32 v[68:69], v[68:69], v[102:103]
	s_waitcnt lgkmcnt(2)
	v_pk_mul_f32 v[72:73], v[72:73], v[106:107]
	s_waitcnt lgkmcnt(1)
	v_pk_mul_f32 v[76:77], v[76:77], v[110:111]
	s_waitcnt lgkmcnt(0)
	v_pk_mul_f32 v[80:81], v[80:81], v[180:181]
	v_pk_mul_f32 v[78:79], v[78:79], v[178:179]
	v_pk_mul_f32 v[74:75], v[74:75], v[108:109]
	v_pk_mul_f32 v[70:71], v[70:71], v[104:105]
	v_pk_mul_f32 v[66:67], v[66:67], v[100:101]
	v_pk_mul_f32 v[64:65], v[64:65], v[180:181]
	v_pk_mul_f32 v[60:61], v[60:61], v[110:111]
	v_pk_mul_f32 v[56:57], v[56:57], v[106:107]
	v_pk_mul_f32 v[52:53], v[52:53], v[102:103]
	v_pk_mul_f32 v[62:63], v[62:63], v[178:179]
	v_pk_mul_f32 v[58:59], v[58:59], v[108:109]
	v_pk_mul_f32 v[54:55], v[54:55], v[104:105]
	v_pk_mul_f32 v[50:51], v[50:51], v[100:101]
	v_pk_mul_f32 v[48:49], v[48:49], v[180:181]
	v_pk_mul_f32 v[44:45], v[44:45], v[110:111]
	v_pk_mul_f32 v[40:41], v[40:41], v[106:107]
	v_pk_mul_f32 v[36:37], v[36:37], v[102:103]
	v_pk_mul_f32 v[46:47], v[46:47], v[178:179]
	v_pk_mul_f32 v[42:43], v[42:43], v[108:109]
	v_pk_mul_f32 v[38:39], v[38:39], v[104:105]
	v_pk_mul_f32 v[34:35], v[34:35], v[100:101]
	v_pk_mul_f32 v[32:33], v[32:33], v[180:181]
	v_pk_mul_f32 v[28:29], v[28:29], v[110:111]
	v_pk_mul_f32 v[24:25], v[24:25], v[106:107]
	v_pk_mul_f32 v[20:21], v[20:21], v[102:103]
	v_pk_mul_f32 v[30:31], v[30:31], v[178:179]
	v_pk_mul_f32 v[26:27], v[26:27], v[108:109]
	v_pk_mul_f32 v[22:23], v[22:23], v[104:105]
	v_pk_mul_f32 v[18:19], v[18:19], v[100:101]
	s_branch .LBB0_555

; #define QK_LD(d) do { const int a_ = kb + (((d) * 32 + hb) ^ xs); B0[d] = lds_rd128<0>(a_); B1[d] = lds_rd128<8192>(a_); Q[d] = lds_rd128<(d) * 1024>(qb); } while (0)
; #define QK_MM(d, W) do { asm volatile("s_waitcnt lgkmcnt(" #W ")" : "+v"(B0[d]), "+v"(B1[d]), "+v"(Q[d]) :: "memory"); \
;     p0 = __builtin_amdgcn_mfma_f32_32x32x16_bf16(B0[d], Q[d], (d) == 0 ? zv : p0, 0, 0, 0); p1 = __builtin_amdgcn_mfma_f32_32x32x16_bf16(B1[d], Q[d], (d) == 0 ? zv : p1, 0, 0, 0); } while (0)
; __device__ __forceinline__ void qkt128(f32x16& p0, f32x16& p1, const char* Ks, const char* Ql, int r32, int hi, const f32x16& zv) {
;   const int kb = (int)(uintptr_t)Ks + r32 * 256, xs = (r32 & 7) << 4, hb = hi * 16, qb = (int)(uintptr_t)Ql;
;   bf16x8 B0[8], B1[8], Q[8];
;     ...
;   QK_LD(0); QK_LD(1); QK_LD(2);
;   QK_MM(0, 6); QK_LD(3); QK_MM(1, 6); QK_LD(4); QK_MM(2, 6); QK_LD(5); QK_MM(3, 6); QK_LD(6); QK_MM(4, 6); QK_LD(7); QK_MM(5, 6); QK_MM(6, 3); QK_MM(7, 0);
.LBB0_559:
	s_andn2_b64 vcc, exec, s[48:49]
	s_mov_b64 s[48:49], -1
	s_waitcnt lgkmcnt(0)
	s_barrier
	s_cbranch_vccnz .LBB0_565
	s_add_i32 s52, s52, -5
	s_cmp_ge_u32 s52, s86
	s_cselect_b64 s[48:49], -1, 0
	s_cmp_lt_u32 s51, s64
	s_cselect_b64 s[52:53], -1, 0
	s_and_b64 s[48:49], s[48:49], s[52:53]
	s_andn2_b64 vcc, exec, s[48:49]
	s_cbranch_vccnz .LBB0_566
	ds_read_b128 v[82:85], v154 offset:0
	ds_read_b128 v[176:179], v154 offset:0x2000
	ds_read_b128 v[180:183], v162 offset:0
	ds_read_b128 v[184:187], v155 offset:0
	ds_read_b128 v[188:191], v155 offset:0x2000
	ds_read_b128 v[196:199], v162 offset:0x400
	ds_read_b128 v[200:203], v156 offset:0
	ds_read_b128 v[204:207], v156 offset:0x2000
	ds_read_b128 v[208:211], v162 offset:0x800
	s_nop 0
	s_waitcnt lgkmcnt(6)
	s_nop 0
	v_mfma_f32_32x32x16_bf16 v[98:113], v[82:85], v[180:183], v[2:17]
	v_mfma_f32_32x32x16_bf16 v[82:97], v[176:179], v[180:183], v[2:17]
	ds_read_b128 v[176:179], v157 offset:0
	ds_read_b128 v[180:183], v157 offset:0x2000
	ds_read_b128 v[212:215], v162 offset:0xc00
	s_waitcnt lgkmcnt(6)
	s_nop 0
	v_mfma_f32_32x32x16_bf16 v[98:113], v[184:187], v[196:199], v[98:113]
	ds_read_b128 v[184:187], v158 offset:0
	v_mfma_f32_32x32x16_bf16 v[82:97], v[188:191], v[196:199], v[82:97]
	ds_read_b128 v[188:191], v158 offset:0x2000
	ds_read_b128 v[196:199], v162 offset:0x1000
	s_waitcnt lgkmcnt(6)
	s_nop 0
	v_mfma_f32_32x32x16_bf16 v[98:113], v[200:203], v[208:211], v[98:113]
	ds_read_b128 v[200:203], v159 offset:0
	v_mfma_f32_32x32x16_bf16 v[82:97], v[204:207], v[208:211], v[82:97]
	ds_read_b128 v[204:207], v159 offset:0x2000
	ds_read_b128 v[208:211], v162 offset:0x1400
	s_waitcnt lgkmcnt(6)
	s_nop 0
	v_mfma_f32_32x32x16_bf16 v[98:113], v[176:179], v[212:215], v[98:113]
	ds_read_b128 v[176:179], v173 offset:0
	v_mfma_f32_32x32x16_bf16 v[82:97], v[180:183], v[212:215], v[82:97]
	ds_read_b128 v[180:183], v173 offset:0x2000
	ds_read_b128 v[212:215], v162 offset:0x1800
	s_waitcnt lgkmcnt(6)
	s_nop 0
	v_mfma_f32_32x32x16_bf16 v[98:113], v[184:187], v[196:199], v[98:113]
	ds_read_b128 v[184:187], v174 offset:0
	v_mfma_f32_32x32x16_bf16 v[82:97], v[188:191], v[196:199], v[82:97]
	ds_read_b128 v[188:191], v174 offset:0x2000
	ds_read_b128 v[196:199], v162 offset:0x1c00
	s_waitcnt lgkmcnt(6)
	s_waitcnt lgkmcnt(3)
	s_nop 0
	s_waitcnt lgkmcnt(0)
	v_mfma_f32_32x32x16_bf16 v[98:113], v[200:203], v[208:211], v[98:113]
	v_mfma_f32_32x32x16_bf16 v[82:97], v[204:207], v[208:211], v[82:97]
	v_mfma_f32_32x32x16_bf16 v[98:113], v[176:179], v[212:215], v[98:113]
	v_mfma_f32_32x32x16_bf16 v[82:97], v[180:183], v[212:215], v[82:97]
	v_mfma_f32_32x32x16_bf16 v[98:113], v[184:187], v[196:199], v[98:113]
	v_mfma_f32_32x32x16_bf16 v[82:97], v[188:191], v[196:199], v[82:97]
	s_nop 11
	ds_read2_b32 v[86:87], v150 offset0:128 offset1:129
	ds_read2_b32 v[88:89], v150 offset0:130 offset1:131
	ds_read2_b32 v[90:91], v150 offset0:136 offset1:137
	ds_read2_b32 v[92:93], v150 offset0:138 offset1:139
	ds_read2_b32 v[178:179], v150 offset0:144 offset1:145
	ds_read2_b32 v[180:181], v150 offset0:146 offset1:147
	ds_read2_b32 v[182:183], v150 offset0:152 offset1:153
	ds_read2_b32 v[184:185], v150 offset0:154 offset1:155
	ds_read2_b32 v[186:187], v150 offset0:160 offset1:161
	ds_read2_b32 v[188:189], v150 offset0:162 offset1:163
	s_waitcnt lgkmcnt(9)
	s_waitcnt lgkmcnt(8)
	s_waitcnt lgkmcnt(7)
	v_add_f32_e32 v86, v98, v86
	v_cndmask_b32_e64 v176, v1, v86, s[4:5]
	v_add_f32_e32 v86, v99, v87
	v_cndmask_b32_e64 v175, v1, v86, s[6:7]
	v_add_f32_e32 v86, v100, v88
	v_cndmask_b32_e64 v99, v1, v86, s[8:9]
	v_add_f32_e32 v86, v101, v89
	v_cndmask_b32_e64 v98, v1, v86, s[10:11]
	v_add_f32_e32 v86, v102, v90
	v_cndmask_b32_e64 v97, v1, v86, s[12:13]
	v_add_f32_e32 v86, v103, v91
	s_waitcnt lgkmcnt(6)
	s_waitcnt lgkmcnt(5)
	s_waitcnt lgkmcnt(4)
	s_waitcnt lgkmcnt(3)
	s_waitcnt lgkmcnt(2)
	s_waitcnt lgkmcnt(1)
	s_waitcnt lgkmcnt(0)
	v_cndmask_b32_e64 v96, v1, v86, s[14:15]
	v_add_f32_e32 v86, v104, v92
	v_add_f32_e32 v84, v84, v188
	v_add_f32_e32 v85, v85, v189
	v_cndmask_b32_e64 v95, v1, v86, s[16:17]
	v_add_f32_e32 v86, v105, v93
	v_add_f32_e32 v82, v82, v186
	v_add_f32_e32 v83, v83, v187
	v_cndmask_b32_e64 v84, v1, v84, s[42:43]
	v_cndmask_b32_e64 v85, v1, v85, s[44:45]
	v_cndmask_b32_e64 v94, v1, v86, s[18:19]
	v_add_f32_e32 v86, v106, v178
	v_cndmask_b32_e64 v82, v1, v82, s[38:39]
	v_cndmask_b32_e64 v83, v1, v83, s[40:41]
	v_max_f32_e32 v100, v84, v85
	v_cndmask_b32_e64 v93, v1, v86, s[20:21]
	v_add_f32_e32 v86, v107, v179
	v_max3_f32 v100, v82, v83, v100
	v_cndmask_b32_e64 v92, v1, v86, s[22:23]
	v_add_f32_e32 v86, v108, v180
	v_max3_f32 v100, v100, v176, v175
	v_cndmask_b32_e64 v91, v1, v86, s[24:25]
	v_add_f32_e32 v86, v109, v181
	v_max3_f32 v100, v100, v99, v98
	v_cndmask_b32_e64 v90, v1, v86, s[26:27]
	v_add_f32_e32 v86, v110, v182
	v_max3_f32 v100, v100, v97, v96
	v_cndmask_b32_e64 v89, v1, v86, s[28:29]
	v_add_f32_e32 v86, v111, v183
	v_max3_f32 v100, v100, v95, v94
	v_cndmask_b32_e64 v88, v1, v86, s[30:31]
	v_add_f32_e32 v86, v112, v184
	v_max3_f32 v100, v100, v93, v92
	v_cndmask_b32_e64 v87, v1, v86, s[34:35]
	v_add_f32_e32 v86, v113, v185
	v_max3_f32 v100, v100, v91, v90
	v_cndmask_b32_e64 v86, v1, v86, s[36:37]
	v_max3_f32 v100, v100, v89, v88
	v_max3_f32 v100, v100, v87, v86
	v_mov_b32_e32 v101, v100
	s_nop 1
	v_permlane32_swap_b32_e32 v100, v101
	v_max_f32_e32 v101, v101, v101
	v_max_f32_e32 v100, v100, v100
	v_max_f32_e32 v100, v100, v101
	v_sub_f32_e32 v101, v100, v171
	v_cmp_ge_f32_e32 vcc, s88, v101
	s_cmp_eq_u64 vcc, exec
	s_cbranch_scc1 .LBB0_567
	v_max_f32_e32 v100, v100, v100
	v_max_f32_e32 v101, v171, v171
	v_max_f32_e32 v170, v101, v100
	v_sub_f32_e32 v100, v171, v170
	v_exp_f32_e32 v100, v100
	v_cmp_eq_f32_e32 vcc, 0xf149f2ca, v171
	s_cmp_eq_u64 vcc, exec
	s_cbranch_scc1 .LBB0_568
	s_and_saveexec_b64 s[48:49], s[46:47]
	ds_write_b32 v152, v100 offset:128
	s_or_b64 exec, exec, s[48:49]
	s_waitcnt lgkmcnt(0)
	v_mul_f32_e32 v169, v169, v100
	ds_read_b128 v[100:103], v153 offset:128
	ds_read_b128 v[104:107], v153 offset:160
	ds_read_b128 v[108:111], v153 offset:192
	ds_read_b128 v[178:181], v153 offset:224
	s_waitcnt lgkmcnt(3)
	v_pk_mul_f32 v[68:69], v[68:69], v[102:103]
	s_waitcnt lgkmcnt(2)
	v_pk_mul_f32 v[72:73], v[72:73], v[106:107]
	s_waitcnt lgkmcnt(1)
	v_pk_mul_f32 v[76:77], v[76:77], v[110:111]
	s_waitcnt lgkmcnt(0)
	v_pk_mul_f32 v[80:81], v[80:81], v[180:181]
	v_pk_mul_f32 v[78:79], v[78:79], v[178:179]
	v_pk_mul_f32 v[74:75], v[74:75], v[108:109]
	v_pk_mul_f32 v[70:71], v[70:71], v[104:105]
	v_pk_mul_f32 v[66:67], v[66:67], v[100:101]
	v_pk_mul_f32 v[64:65], v[64:65], v[180:181]
	v_pk_mul_f32 v[60:61], v[60:61], v[110:111]
	v_pk_mul_f32 v[56:57], v[56:57], v[106:107]
	v_pk_mul_f32 v[52:53], v[52:53], v[102:103]
	v_pk_mul_f32 v[62:63], v[62:63], v[178:179]
	v_pk_mul_f32 v[58:59], v[58:59], v[108:109]
	v_pk_mul_f32 v[54:55], v[54:55], v[104:105]
	v_pk_mul_f32 v[50:51], v[50:51], v[100:101]
	v_pk_mul_f32 v[48:49], v[48:49], v[180:181]
	v_pk_mul_f32 v[44:45], v[44:45], v[110:111]
	v_pk_mul_f32 v[40:41], v[40:41], v[106:107]
	v_pk_mul_f32 v[36:37], v[36:37], v[102:103]
	v_pk_mul_f32 v[46:47], v[46:47], v[178:179]
	v_pk_mul_f32 v[42:43], v[42:43], v[108:109]
	v_pk_mul_f32 v[38:39], v[38:39], v[104:105]
	v_pk_mul_f32 v[34:35], v[34:35], v[100:101]
	v_pk_mul_f32 v[32:33], v[32:33], v[180:181]
	v_pk_mul_f32 v[28:29], v[28:29], v[110:111]
	v_pk_mul_f32 v[24:25], v[24:25], v[106:107]
	v_pk_mul_f32 v[20:21], v[20:21], v[102:103]
	v_pk_mul_f32 v[30:31], v[30:31], v[178:179]
	v_pk_mul_f32 v[26:27], v[26:27], v[108:109]
	v_pk_mul_f32 v[22:23], v[22:23], v[104:105]
	v_pk_mul_f32 v[18:19], v[18:19], v[100:101]
	s_branch .LBB0_568
